# G1-odd: prefetch second half-tile's bias during first half's epilogue (ahead of its stores), reuse rs values
# speedup vs baseline: 1.0753x; 1.0038x over previous
.LBB0_280:
	s_barrier
	s_waitcnt vmcnt(9)
	ds_write_b128 v186, v[142:145]
	ds_write_b128 v186, v[134:137] offset:4608
	ds_write_b128 v186, v[130:133] offset:9216
	s_waitcnt vmcnt(7)
	ds_write_b128 v186, v[146:149] offset:13824
	ds_write_b128 v186, v[138:141] offset:18432
	s_waitcnt vmcnt(6)
	ds_write_b128 v186, v[150:153] offset:23040
	s_waitcnt vmcnt(5)
	ds_write_b128 v186, v[154:157] offset:27648
	s_waitcnt vmcnt(4)
	ds_write_b128 v186, v[158:161] offset:32256
	s_waitcnt vmcnt(3)
	ds_write_b128 v186, v[162:165] offset:36864
	s_waitcnt vmcnt(2)
	ds_write_b128 v186, v[166:169] offset:41472
	s_waitcnt vmcnt(1)
	ds_write_b128 v186, v[170:173] offset:46080
	s_waitcnt vmcnt(0)
	ds_write_b128 v186, v[174:177] offset:50688
	s_waitcnt lgkmcnt(0)
	s_barrier
	s_setprio 2
	s_mov_b32 vcc_hi, 0
	ds_read_b128 v[244:247], v230
	ds_read_b128 v[210:213], v231 offset:18432
	ds_read_b128 v[248:251], v230 offset:4608
	ds_read_b128 v[214:217], v231 offset:23040
	ds_read_b128 v[218:221], v231 offset:27648
	ds_read_b128 v[222:225], v231 offset:32256
	s_waitcnt lgkmcnt(4)
	v_mfma_f32_32x32x16_bf16 v[114:129], v[210:213], v[244:247], v[114:129]
	s_add_u32 vcc_lo, s22, 0xd400080
	v_lshl_add_u64 v[240:241], v[204:205], 0, vcc
	global_load_dwordx4 v[142:145], v[240:241], off
	ds_read_b128 v[252:255], v230 offset:32
	s_waitcnt lgkmcnt(4)
	v_mfma_f32_32x32x16_bf16 v[82:97], v[210:213], v[248:251], v[82:97]
	s_add_u32 vcc_lo, s22, 0xd410080
	v_lshl_add_u64 v[178:179], v[204:205], 0, vcc
	global_load_dwordx4 v[134:137], v[178:179], off
	ds_read_b128 v[210:213], v231 offset:18464
	s_waitcnt lgkmcnt(4)
	v_mfma_f32_32x32x16_bf16 v[98:113], v[214:217], v[244:247], v[98:113]
	s_add_u32 vcc_lo, s22, 0xd420080
	v_lshl_add_u64 v[240:241], v[204:205], 0, vcc
	global_load_dwordx4 v[130:133], v[240:241], off
	ds_read_b128 v[232:235], v230 offset:4640
	v_mfma_f32_32x32x16_bf16 v[66:81], v[214:217], v[248:251], v[66:81]
	s_add_u32 vcc_lo, s22, 0xd430080
	v_lshl_add_u64 v[178:179], v[204:205], 0, vcc
	global_load_dwordx4 v[146:149], v[178:179], off
	ds_read_b128 v[214:217], v231 offset:23072
	s_waitcnt lgkmcnt(5)
	v_mfma_f32_32x32x16_bf16 v[50:65], v[218:221], v[244:247], v[50:65]
	s_add_u32 vcc_lo, s22, 0xac00080
	v_lshl_add_u64 v[240:241], v[202:203], 0, vcc
	global_load_dwordx4 v[138:141], v[240:241], off
	v_mfma_f32_32x32x16_bf16 v[18:33], v[218:221], v[248:251], v[18:33]
	s_add_u32 vcc_lo, s22, 0xac10080
	v_lshl_add_u64 v[178:179], v[202:203], 0, vcc
	global_load_dwordx4 v[150:153], v[178:179], off
	ds_read_b128 v[218:221], v231 offset:27680
	s_waitcnt lgkmcnt(5)
	v_mfma_f32_32x32x16_bf16 v[34:49], v[222:225], v[244:247], v[34:49]
	s_add_u32 vcc_lo, s22, 0xac20080
	v_lshl_add_u64 v[240:241], v[202:203], 0, vcc
	global_load_dwordx4 v[154:157], v[240:241], off
	v_mfma_f32_32x32x16_bf16 v[2:17], v[222:225], v[248:251], v[2:17]
	s_add_u32 vcc_lo, s22, 0xac30080
	v_lshl_add_u64 v[178:179], v[202:203], 0, vcc
	global_load_dwordx4 v[158:161], v[178:179], off
	ds_read_b128 v[222:225], v231 offset:32288
	s_waitcnt lgkmcnt(4)
	v_mfma_f32_32x32x16_bf16 v[114:129], v[210:213], v[252:255], v[114:129]
	s_add_u32 vcc_lo, s22, 0xac40080
	v_lshl_add_u64 v[240:241], v[202:203], 0, vcc
	global_load_dwordx4 v[162:165], v[240:241], off
	ds_read_b128 v[244:247], v230 offset:64
	s_waitcnt lgkmcnt(4)
	v_mfma_f32_32x32x16_bf16 v[82:97], v[210:213], v[232:235], v[82:97]
	s_add_u32 vcc_lo, s22, 0xac50080
	v_lshl_add_u64 v[178:179], v[202:203], 0, vcc
	global_load_dwordx4 v[166:169], v[178:179], off
	ds_read_b128 v[210:213], v231 offset:18496
	s_waitcnt lgkmcnt(4)
	v_mfma_f32_32x32x16_bf16 v[98:113], v[214:217], v[252:255], v[98:113]
	s_add_u32 vcc_lo, s22, 0xac60080
	v_lshl_add_u64 v[240:241], v[202:203], 0, vcc
	global_load_dwordx4 v[170:173], v[240:241], off
	ds_read_b128 v[248:251], v230 offset:4672
	v_mfma_f32_32x32x16_bf16 v[66:81], v[214:217], v[232:235], v[66:81]
	s_add_u32 vcc_lo, s22, 0xac70080
	v_lshl_add_u64 v[178:179], v[202:203], 0, vcc
	global_load_dwordx4 v[174:177], v[178:179], off
	ds_read_b128 v[214:217], v231 offset:23104
	s_waitcnt lgkmcnt(5)
	v_mfma_f32_32x32x16_bf16 v[50:65], v[218:221], v[252:255], v[50:65]
	v_mfma_f32_32x32x16_bf16 v[18:33], v[218:221], v[232:235], v[18:33]
	ds_read_b128 v[218:221], v231 offset:27712
	s_waitcnt lgkmcnt(5)
	v_mfma_f32_32x32x16_bf16 v[34:49], v[222:225], v[252:255], v[34:49]
	v_mfma_f32_32x32x16_bf16 v[2:17], v[222:225], v[232:235], v[2:17]
	ds_read_b128 v[222:225], v231 offset:32320
	s_waitcnt lgkmcnt(4)
	v_mfma_f32_32x32x16_bf16 v[114:129], v[210:213], v[244:247], v[114:129]
	ds_read_b128 v[252:255], v230 offset:96
	s_waitcnt lgkmcnt(4)
	v_mfma_f32_32x32x16_bf16 v[82:97], v[210:213], v[248:251], v[82:97]
	ds_read_b128 v[210:213], v231 offset:18528
	s_waitcnt lgkmcnt(4)
	v_mfma_f32_32x32x16_bf16 v[98:113], v[214:217], v[244:247], v[98:113]
	ds_read_b128 v[232:235], v230 offset:4704
	v_mfma_f32_32x32x16_bf16 v[66:81], v[214:217], v[248:251], v[66:81]
	ds_read_b128 v[214:217], v231 offset:23136
	s_waitcnt lgkmcnt(5)
	v_mfma_f32_32x32x16_bf16 v[50:65], v[218:221], v[244:247], v[50:65]
	v_mfma_f32_32x32x16_bf16 v[18:33], v[218:221], v[248:251], v[18:33]
	ds_read_b128 v[218:221], v231 offset:27744
	s_waitcnt lgkmcnt(5)
	v_mfma_f32_32x32x16_bf16 v[34:49], v[222:225], v[244:247], v[34:49]
	v_mfma_f32_32x32x16_bf16 v[2:17], v[222:225], v[248:251], v[2:17]
	ds_read_b128 v[222:225], v231 offset:32352
	s_waitcnt lgkmcnt(4)
	v_mfma_f32_32x32x16_bf16 v[114:129], v[210:213], v[252:255], v[114:129]
	s_waitcnt lgkmcnt(3)
	v_mfma_f32_32x32x16_bf16 v[82:97], v[210:213], v[232:235], v[82:97]
	s_waitcnt lgkmcnt(2)
	v_mfma_f32_32x32x16_bf16 v[98:113], v[214:217], v[252:255], v[98:113]
	v_mfma_f32_32x32x16_bf16 v[66:81], v[214:217], v[232:235], v[66:81]
	s_waitcnt lgkmcnt(1)
	v_mfma_f32_32x32x16_bf16 v[50:65], v[218:221], v[252:255], v[50:65]
	v_mfma_f32_32x32x16_bf16 v[18:33], v[218:221], v[232:235], v[18:33]
	s_waitcnt lgkmcnt(0)
	v_mfma_f32_32x32x16_bf16 v[34:49], v[222:225], v[252:255], v[34:49]
	v_mfma_f32_32x32x16_bf16 v[2:17], v[222:225], v[232:235], v[2:17]
	s_setprio 0
	s_add_u32 s22, s22, 0x80
	s_addc_u32 s23, s23, 0
	s_cmpk_eq_i32 s22, 0x780
	s_cbranch_scc0 .LBB0_280
	v_mov_b32_e32 v210, 64
	v_xor_b32_e32 v211, 32, v209
	v_xor_b32_e32 v212, 16, v209
	v_xor_b32_e32 v213, 8, v209
	v_xor_b32_e32 v214, 4, v209
	v_xor_b32_e32 v215, 2, v209
	v_xor_b32_e32 v216, 1, v209
	v_mov_b32_e32 v217, 2
	v_bfrev_b32_e32 v218, 32
	v_bfrev_b32_e32 v219, 64
	v_mov_b32_e32 v220, 0xff800000
	v_mov_b32_e32 v221, 0x80
	v_mov_b32_e32 v222, 0x200
	v_mov_b32_e32 v223, 0x2000
	v_mov_b32_e32 v224, 0x461c4000
	v_mov_b32_e32 v225, 0x63
	v_mov_b64_e32 v[178:179], 0xf500000
	s_setprio 0
	s_barrier
	s_waitcnt vmcnt(11)
	ds_write_b128 v186, v[142:145]
	s_waitcnt vmcnt(10)
	ds_write_b128 v186, v[134:137] offset:4608
	s_waitcnt vmcnt(9)
	ds_write_b128 v186, v[130:133] offset:9216
	s_waitcnt vmcnt(8)
	ds_write_b128 v186, v[146:149] offset:13824
	s_waitcnt vmcnt(7)
	ds_write_b128 v186, v[138:141] offset:18432
	s_waitcnt vmcnt(6)
	ds_write_b128 v186, v[150:153] offset:23040
	s_waitcnt vmcnt(5)
	ds_write_b128 v186, v[154:157] offset:27648
	s_waitcnt vmcnt(4)
	ds_write_b128 v186, v[158:161] offset:32256
	s_waitcnt vmcnt(3)
	ds_write_b128 v186, v[162:165] offset:36864
	s_waitcnt vmcnt(2)
	ds_write_b128 v186, v[166:169] offset:41472
	s_waitcnt vmcnt(1)
	ds_write_b128 v186, v[170:173] offset:46080
	s_waitcnt vmcnt(0)
	ds_write_b128 v186, v[174:177] offset:50688
	s_waitcnt lgkmcnt(0)
	s_setprio 0
	s_barrier
	s_setprio 1
	ds_read_b128 v[130:133], v230 offset:4608
	ds_read_b128 v[134:137], v231 offset:23040
	ds_read_b128 v[138:141], v230
	ds_read_b128 v[142:145], v230 offset:32
	ds_read_b128 v[146:149], v231 offset:18432
	ds_read_b128 v[150:153], v231 offset:18464
	s_waitcnt lgkmcnt(1)
	v_mfma_f32_32x32x16_bf16 v[114:129], v[146:149], v[138:141], v[114:129]
	v_mfma_f32_32x32x16_bf16 v[82:97], v[146:149], v[130:133], v[82:97]
	v_mfma_f32_32x32x16_bf16 v[98:113], v[134:137], v[138:141], v[98:113]
	v_mfma_f32_32x32x16_bf16 v[66:81], v[134:137], v[130:133], v[66:81]
	ds_read_b128 v[134:137], v231 offset:27648
	ds_read_b128 v[146:149], v231 offset:32256
	s_waitcnt lgkmcnt(1)
	v_mfma_f32_32x32x16_bf16 v[50:65], v[134:137], v[138:141], v[50:65]
	v_mfma_f32_32x32x16_bf16 v[18:33], v[134:137], v[130:133], v[18:33]
	s_waitcnt lgkmcnt(0)
	v_mfma_f32_32x32x16_bf16 v[2:17], v[146:149], v[130:133], v[2:17]
	ds_read_b128 v[130:133], v230 offset:4640
	ds_read_b128 v[134:137], v231 offset:23072
	v_mfma_f32_32x32x16_bf16 v[34:49], v[146:149], v[138:141], v[34:49]
	s_waitcnt lgkmcnt(0)
	v_mfma_f32_32x32x16_bf16 v[98:113], v[134:137], v[142:145], v[98:113]
	v_mfma_f32_32x32x16_bf16 v[66:81], v[134:137], v[130:133], v[66:81]
	ds_read_b128 v[134:137], v231 offset:27680
	ds_read_b128 v[138:141], v231 offset:32288
	v_mfma_f32_32x32x16_bf16 v[114:129], v[150:153], v[142:145], v[114:129]
	v_mfma_f32_32x32x16_bf16 v[82:97], v[150:153], v[130:133], v[82:97]
	s_waitcnt lgkmcnt(1)
	v_mfma_f32_32x32x16_bf16 v[50:65], v[134:137], v[142:145], v[50:65]
	v_mfma_f32_32x32x16_bf16 v[18:33], v[134:137], v[130:133], v[18:33]
	s_waitcnt lgkmcnt(0)
	v_mfma_f32_32x32x16_bf16 v[34:49], v[138:141], v[142:145], v[34:49]
	v_mfma_f32_32x32x16_bf16 v[2:17], v[138:141], v[130:133], v[2:17]
	ds_read_b128 v[130:133], v230 offset:64
	ds_read_b128 v[134:137], v230 offset:4672
	ds_read_b128 v[138:141], v231 offset:18496
	ds_read_b128 v[142:145], v231 offset:23104
	s_waitcnt lgkmcnt(1)
	v_mfma_f32_32x32x16_bf16 v[114:129], v[138:141], v[130:133], v[114:129]
	v_mfma_f32_32x32x16_bf16 v[82:97], v[138:141], v[134:137], v[82:97]
	s_waitcnt lgkmcnt(0)
	v_mfma_f32_32x32x16_bf16 v[98:113], v[142:145], v[130:133], v[98:113]
	v_mfma_f32_32x32x16_bf16 v[66:81], v[142:145], v[134:137], v[66:81]
	ds_read_b128 v[138:141], v231 offset:27712
	ds_read_b128 v[142:145], v231 offset:32320
	s_waitcnt lgkmcnt(1)
	v_mfma_f32_32x32x16_bf16 v[50:65], v[138:141], v[130:133], v[50:65]
	v_mfma_f32_32x32x16_bf16 v[18:33], v[138:141], v[134:137], v[18:33]
	s_waitcnt lgkmcnt(0)
	v_mfma_f32_32x32x16_bf16 v[34:49], v[142:145], v[130:133], v[34:49]
	v_mfma_f32_32x32x16_bf16 v[2:17], v[142:145], v[134:137], v[2:17]
	ds_read_b128 v[130:133], v230 offset:96
	ds_read_b128 v[134:137], v230 offset:4704
	ds_read_b128 v[138:141], v231 offset:18528
	ds_read_b128 v[142:145], v231 offset:23136
	s_waitcnt lgkmcnt(1)
	v_mfma_f32_32x32x16_bf16 v[114:129], v[138:141], v[130:133], v[114:129]
	v_mfma_f32_32x32x16_bf16 v[82:97], v[138:141], v[134:137], v[82:97]
	s_waitcnt lgkmcnt(0)
	v_mfma_f32_32x32x16_bf16 v[98:113], v[142:145], v[130:133], v[98:113]
	v_mfma_f32_32x32x16_bf16 v[66:81], v[142:145], v[134:137], v[66:81]
	ds_read_b128 v[138:141], v231 offset:27744
	ds_read_b128 v[142:145], v231 offset:32352
	s_waitcnt lgkmcnt(0)
	s_setprio 0
	s_barrier
	v_mfma_f32_32x32x16_bf16 v[18:33], v[138:141], v[134:137], v[18:33]
	v_mfma_f32_32x32x16_bf16 v[2:17], v[142:145], v[134:137], v[2:17]
	v_add_u32_e32 v136, s2, v187
	v_ashrrev_i32_e32 v134, 11, v136
	v_and_b32_e32 v157, 0x7c0, v136
	v_mfma_f32_32x32x16_bf16 v[50:65], v[138:141], v[130:133], v[50:65]
	v_or_b32_e32 v138, s3, v191
	v_ashrrev_i32_e32 v139, 31, v138
	v_ashrrev_i32_e32 v159, 6, v138
	v_mfma_f32_32x32x16_bf16 v[34:49], v[142:145], v[130:133], v[34:49]
	v_or_b32_e32 v132, v136, v189
	v_ashrrev_i32_e32 v133, 31, v132
	v_lshl_add_u64 v[142:143], v[132:133], 2, s[40:41]
	global_load_dword v132, v[142:143], off
	v_lshlrev_b32_e32 v130, 12, v134
	v_ashrrev_i32_e32 v131, 31, v130
	v_lshl_add_u64 v[130:131], v[130:131], 2, s[42:43]
	v_lshl_add_u64 v[130:131], v[138:139], 2, v[130:131]
	v_lshl_add_u64 v[140:141], v[130:131], 0, v[0:1]
	s_waitcnt vmcnt(0)
	v_fmamk_f32 v132, v132, 0x3a800000, v208
	v_cmp_gt_f32_e32 vcc, s84, v132
	v_mul_f32_e32 v133, 0x4b800000, v132
	s_nop 0
	v_cndmask_b32_e32 v132, v132, v133, vcc
	v_rsq_f32_e32 v132, v132
	s_nop 0
	v_mul_f32_e32 v133, 0x45800000, v132
	v_cndmask_b32_e32 v156, v132, v133, vcc
	v_mov_b32_e32 v240, v156
	global_load_dword v132, v[142:143], off offset:128
	s_waitcnt vmcnt(0)
	v_fmamk_f32 v132, v132, 0x3a800000, v208
	v_cmp_gt_f32_e32 vcc, s84, v132
	v_mul_f32_e32 v133, 0x4b800000, v132
	s_nop 0
	v_cndmask_b32_e32 v132, v132, v133, vcc
	v_rsq_f32_e32 v132, v132
	s_nop 0
	v_mul_f32_e32 v133, 0x45800000, v132
	v_cndmask_b32_e32 v158, v132, v133, vcc
	v_mov_b32_e32 v241, v158
	global_load_dwordx4 v[150:153], v[140:141], off
	global_load_dwordx4 v[160:163], v[140:141], off offset:32
	global_load_dwordx4 v[164:167], v[140:141], off offset:64
	global_load_dwordx4 v[130:133], v[140:141], off offset:96
	global_load_dwordx4 v[168:171], v[140:141], off offset:128
	v_cmp_lt_i32_e32 vcc, 31, v159
	s_waitcnt vmcnt(4)
	v_pk_fma_f32 v[148:149], v[114:115], v[156:157], v[150:151] op_sel_hi:[1,0,1]
	v_pk_fma_f32 v[114:115], v[82:83], v[158:159], v[150:151] op_sel_hi:[1,0,1]
	v_pk_fma_f32 v[150:151], v[116:117], v[156:157], v[152:153] op_sel_hi:[1,0,1]
	v_pk_fma_f32 v[116:117], v[84:85], v[158:159], v[152:153] op_sel_hi:[1,0,1]
	s_waitcnt vmcnt(0)
	v_pk_fma_f32 v[144:145], v[98:99], v[156:157], v[168:169] op_sel_hi:[1,0,1]
	v_pk_fma_f32 v[98:99], v[66:67], v[158:159], v[168:169] op_sel_hi:[1,0,1]
	v_pk_fma_f32 v[146:147], v[100:101], v[156:157], v[170:171] op_sel_hi:[1,0,1]
	v_pk_fma_f32 v[100:101], v[68:69], v[158:159], v[170:171] op_sel_hi:[1,0,1]
	global_load_dwordx4 v[66:69], v[140:141], off offset:160
	v_pk_fma_f32 v[152:153], v[118:119], v[156:157], v[160:161] op_sel_hi:[1,0,1]
	v_pk_fma_f32 v[154:155], v[120:121], v[156:157], v[162:163] op_sel_hi:[1,0,1]
	v_pk_fma_f32 v[122:123], v[122:123], v[156:157], v[164:165] op_sel_hi:[1,0,1]
	v_pk_fma_f32 v[124:125], v[124:125], v[156:157], v[166:167] op_sel_hi:[1,0,1]
	v_pk_fma_f32 v[126:127], v[126:127], v[156:157], v[130:131] op_sel_hi:[1,0,1]
	v_pk_fma_f32 v[84:85], v[94:95], v[158:159], v[130:131] op_sel_hi:[1,0,1]
	v_pk_fma_f32 v[128:129], v[128:129], v[156:157], v[132:133] op_sel_hi:[1,0,1]
	s_waitcnt vmcnt(0)
	v_pk_fma_f32 v[118:119], v[102:103], v[156:157], v[66:67] op_sel_hi:[1,0,1]
	v_pk_fma_f32 v[70:71], v[70:71], v[158:159], v[66:67] op_sel_hi:[1,0,1]
	v_pk_fma_f32 v[120:121], v[104:105], v[156:157], v[68:69] op_sel_hi:[1,0,1]
	v_pk_fma_f32 v[72:73], v[72:73], v[158:159], v[68:69] op_sel_hi:[1,0,1]
	global_load_dwordx4 v[66:69], v[140:141], off offset:192
	v_pk_fma_f32 v[102:103], v[86:87], v[158:159], v[160:161] op_sel_hi:[1,0,1]
	v_pk_fma_f32 v[104:105], v[88:89], v[158:159], v[162:163] op_sel_hi:[1,0,1]
	v_pk_fma_f32 v[88:89], v[90:91], v[158:159], v[164:165] op_sel_hi:[1,0,1]
	v_pk_fma_f32 v[90:91], v[92:93], v[158:159], v[166:167] op_sel_hi:[1,0,1]
	v_pk_fma_f32 v[86:87], v[96:97], v[158:159], v[132:133] op_sel_hi:[1,0,1]
	s_waitcnt vmcnt(0)
	v_pk_fma_f32 v[106:107], v[106:107], v[156:157], v[66:67] op_sel_hi:[1,0,1]
	v_pk_fma_f32 v[66:67], v[74:75], v[158:159], v[66:67] op_sel_hi:[1,0,1]
	v_pk_fma_f32 v[108:109], v[108:109], v[156:157], v[68:69] op_sel_hi:[1,0,1]
	v_pk_fma_f32 v[68:69], v[76:77], v[158:159], v[68:69] op_sel_hi:[1,0,1]
	global_load_dwordx4 v[74:77], v[140:141], off offset:224
	global_load_dwordx4 v[236:239], v[140:141], off offset:256
	global_load_dwordx4 v[244:247], v[140:141], off offset:288
	global_load_dwordx4 v[248:251], v[140:141], off offset:320
	global_load_dwordx4 v[252:255], v[140:141], off offset:352
	global_load_dwordx4 v[210:213], v[140:141], off offset:384
	global_load_dwordx4 v[214:217], v[140:141], off offset:416
	global_load_dwordx4 v[222:225], v[140:141], off offset:448
	global_load_dwordx4 v[232:235], v[140:141], off offset:480
	s_waitcnt vmcnt(0)
	v_pk_fma_f32 v[110:111], v[110:111], v[156:157], v[74:75] op_sel_hi:[1,0,1]
	v_pk_fma_f32 v[82:83], v[78:79], v[158:159], v[74:75] op_sel_hi:[1,0,1]
	v_pk_fma_f32 v[94:95], v[112:113], v[156:157], v[76:77] op_sel_hi:[1,0,1]
	v_pk_fma_f32 v[80:81], v[80:81], v[158:159], v[76:77] op_sel_hi:[1,0,1]
	s_and_saveexec_b64 s[2:3], vcc
	s_xor_b64 s[2:3], exec, s[2:3]
	s_cbranch_execz .LBB0_287
	v_cmp_lt_u32_e32 vcc, 47, v159
	v_cvt_pk_bf16_f32 v74, v152, s0
	v_cvt_pk_bf16_f32 v75, v153, s0
	v_cvt_pk_bf16_f32 v76, v154, s0
	v_cvt_pk_bf16_f32 v77, v155, s0
	s_and_saveexec_b64 s[8:9], vcc
	s_xor_b64 s[22:23], exec, s[8:9]
	s_cbranch_execz .LBB0_284
	s_mov_b32 s8, 0x5040100
	v_cvt_pk_bf16_f32 v93, v150, v151
	v_cvt_pk_bf16_f32 v92, v148, v149
	v_perm_b32 v77, v77, v76, s8
	v_perm_b32 v76, v75, v74, s8
	ds_write2_b64 v226, v[92:93], v[76:77] offset1:2
	v_cvt_pk_bf16_f32 v75, v124, v125
	v_cvt_pk_bf16_f32 v74, v122, v123
	v_cvt_pk_bf16_f32 v77, v128, v129
	v_cvt_pk_bf16_f32 v76, v126, v127
	ds_write2_b64 v226, v[74:75], v[76:77] offset0:4 offset1:6
	v_cvt_pk_bf16_f32 v75, v146, v147
	v_cvt_pk_bf16_f32 v74, v144, v145
	v_cvt_pk_bf16_f32 v77, v120, v121
	v_cvt_pk_bf16_f32 v76, v118, v119
	ds_write2_b64 v226, v[74:75], v[76:77] offset0:8 offset1:10
	v_cvt_pk_bf16_f32 v75, v108, v109
	v_cvt_pk_bf16_f32 v74, v106, v107
	v_cvt_pk_bf16_f32 v77, v94, v95
	v_cvt_pk_bf16_f32 v76, v110, v111
	v_ashrrev_i32_e32 v137, 31, v136
	ds_write2_b64 v226, v[74:75], v[76:77] offset0:12 offset1:14
	v_cvt_pk_bf16_f32 v75, v116, v117
	v_cvt_pk_bf16_f32 v74, v114, v115
	v_cvt_pk_bf16_f32 v77, v104, v105
	v_cvt_pk_bf16_f32 v76, v102, v103
	v_add_u32_e32 v92, 0x1000, v226
	v_lshlrev_b64 v[78:79], 11, v[136:137]
	ds_write2_b64 v92, v[74:75], v[76:77] offset0:64 offset1:66
	v_cvt_pk_bf16_f32 v75, v90, v91
	v_cvt_pk_bf16_f32 v74, v88, v89
	v_cvt_pk_bf16_f32 v77, v86, v87
	v_cvt_pk_bf16_f32 v76, v84, v85
	v_lshl_add_u64 v[78:79], s[38:39], 0, v[78:79]
	v_mov_b32_e32 v139, v1
	ds_write2_b64 v92, v[74:75], v[76:77] offset0:68 offset1:70
	v_cvt_pk_bf16_f32 v75, v100, v101
	v_cvt_pk_bf16_f32 v74, v98, v99
	v_cvt_pk_bf16_f32 v73, v72, v73
	v_cvt_pk_bf16_f32 v72, v70, v71
	v_cvt_pk_bf16_f32 v69, v68, v69
	v_cvt_pk_bf16_f32 v68, v66, v67
	v_cvt_pk_bf16_f32 v67, v80, v81
	v_cvt_pk_bf16_f32 v66, v82, v83
	v_lshl_add_u64 v[78:79], v[138:139], 1, v[78:79]
	ds_write2_b64 v92, v[74:75], v[72:73] offset0:72 offset1:74
	ds_write2_b64 v92, v[68:69], v[66:67] offset0:76 offset1:78
	v_lshlrev_b32_e32 v66, 1, v188
	v_mov_b32_e32 v67, v1
	v_lshl_add_u64 v[66:67], v[78:79], 0, v[66:67]
	v_lshlrev_b32_e32 v68, 1, v180
	v_mov_b32_e32 v69, v1
	v_lshl_add_u64 v[74:75], v[66:67], 0, v[68:69]
	ds_read_b128 v[66:69], v227
	ds_read_b128 v[70:73], v227 offset:1152
	s_mov_b32 s8, 0x7ffe000
	v_add_co_u32_e32 v76, vcc, s8, v74
	s_mov_b32 s8, 0x8002000
	s_nop 0
	v_addc_co_u32_e32 v77, vcc, 0, v75, vcc
	s_waitcnt lgkmcnt(1)
	global_store_dwordx4 v[76:77], v[66:69], off offset:2048
	s_nop 1
	v_add_co_u32_e32 v66, vcc, s8, v74
	s_mov_b32 s8, 0x8006000
	s_nop 0
	v_addc_co_u32_e32 v67, vcc, 0, v75, vcc
	s_waitcnt lgkmcnt(0)
	global_store_dwordx4 v[66:67], v[70:73], off offset:2048
	ds_read_b128 v[66:69], v227 offset:2304
	ds_read_b128 v[70:73], v227 offset:3456
	v_add_co_u32_e32 v76, vcc, s8, v74
	s_mov_b32 s8, 0x800a000
	s_nop 0
	v_addc_co_u32_e32 v77, vcc, 0, v75, vcc
	s_waitcnt lgkmcnt(1)
	global_store_dwordx4 v[76:77], v[66:69], off offset:2048
	s_nop 1
	v_add_co_u32_e32 v66, vcc, s8, v74
	s_mov_b32 s8, 0x800e000
	s_nop 0
	v_addc_co_u32_e32 v67, vcc, 0, v75, vcc
	s_waitcnt lgkmcnt(0)
	global_store_dwordx4 v[66:67], v[70:73], off offset:2048
	ds_read_b128 v[66:69], v227 offset:4608
	ds_read_b128 v[70:73], v227 offset:5760
	v_add_co_u32_e32 v76, vcc, s8, v74
	s_nop 1
	v_addc_co_u32_e32 v77, vcc, 0, v75, vcc
	s_waitcnt lgkmcnt(1)
	global_store_dwordx4 v[76:77], v[66:69], off offset:2048
	s_nop 1
	v_add_co_u32_e32 v66, vcc, 0x8012000, v74
	s_nop 1
	v_addc_co_u32_e32 v67, vcc, 0, v75, vcc
	s_waitcnt lgkmcnt(0)
	global_store_dwordx4 v[66:67], v[70:73], off offset:2048
	ds_read_b128 v[66:69], v227 offset:6912
	ds_read_b128 v[70:73], v227 offset:8064
	v_add_co_u32_e32 v76, vcc, 0x8016000, v74
	s_nop 1
	v_addc_co_u32_e32 v77, vcc, 0, v75, vcc
	s_waitcnt lgkmcnt(1)
	global_store_dwordx4 v[76:77], v[66:69], off offset:2048
	s_nop 1
	v_add_co_u32_e32 v66, vcc, 0x801a000, v74
	s_nop 1
	v_addc_co_u32_e32 v67, vcc, 0, v75, vcc
	s_waitcnt lgkmcnt(0)
	global_store_dwordx4 v[66:67], v[70:73], off offset:2048

.LBB0_293:
	s_or_b64 exec, exec, s[46:47]
	v_mov_b32_e32 v88, v240
	v_mov_b32_e32 v90, v241
	s_waitcnt vmcnt(8)
	v_or_b32_e32 v75, 64, v138
	v_ashrrev_i32_e32 v89, 6, v75
	v_cmp_lt_i32_e32 vcc, 31, v89
	v_pk_fma_f32 v[80:81], v[50:51], v[88:89], v[236:237] op_sel_hi:[1,0,1]
	v_pk_fma_f32 v[50:51], v[18:19], v[90:91], v[236:237] op_sel_hi:[1,0,1]
	v_pk_fma_f32 v[82:83], v[52:53], v[88:89], v[238:239] op_sel_hi:[1,0,1]
	v_pk_fma_f32 v[52:53], v[20:21], v[90:91], v[238:239] op_sel_hi:[1,0,1]
	v_pk_fma_f32 v[70:71], v[34:35], v[88:89], v[210:211] op_sel_hi:[1,0,1]
	v_pk_fma_f32 v[34:35], v[2:3], v[90:91], v[210:211] op_sel_hi:[1,0,1]
	v_pk_fma_f32 v[72:73], v[36:37], v[88:89], v[212:213] op_sel_hi:[1,0,1]
	v_pk_fma_f32 v[36:37], v[4:5], v[90:91], v[212:213] op_sel_hi:[1,0,1]
	v_pk_fma_f32 v[84:85], v[54:55], v[88:89], v[244:245] op_sel_hi:[1,0,1]
	v_pk_fma_f32 v[86:87], v[56:57], v[88:89], v[246:247] op_sel_hi:[1,0,1]
	v_pk_fma_f32 v[20:21], v[26:27], v[90:91], v[248:249] op_sel_hi:[1,0,1]
	v_pk_fma_f32 v[24:25], v[24:25], v[90:91], v[246:247] op_sel_hi:[1,0,1]
	v_pk_fma_f32 v[58:59], v[58:59], v[88:89], v[248:249] op_sel_hi:[1,0,1]
	v_pk_fma_f32 v[18:19], v[30:31], v[90:91], v[252:253] op_sel_hi:[1,0,1]
	v_pk_fma_f32 v[54:55], v[38:39], v[88:89], v[214:215] op_sel_hi:[1,0,1]
	v_pk_fma_f32 v[6:7], v[6:7], v[90:91], v[214:215] op_sel_hi:[1,0,1]
	v_pk_fma_f32 v[56:57], v[40:41], v[88:89], v[216:217] op_sel_hi:[1,0,1]
	v_pk_fma_f32 v[8:9], v[8:9], v[90:91], v[216:217] op_sel_hi:[1,0,1]
	v_pk_fma_f32 v[38:39], v[22:23], v[90:91], v[244:245] op_sel_hi:[1,0,1]
	v_pk_fma_f32 v[22:23], v[28:29], v[90:91], v[250:251] op_sel_hi:[1,0,1]
	v_pk_fma_f32 v[40:41], v[42:43], v[88:89], v[222:223] op_sel_hi:[1,0,1]
	v_pk_fma_f32 v[2:3], v[10:11], v[90:91], v[222:223] op_sel_hi:[1,0,1]
	v_pk_fma_f32 v[26:27], v[44:45], v[88:89], v[224:225] op_sel_hi:[1,0,1]
	v_pk_fma_f32 v[4:5], v[12:13], v[90:91], v[224:225] op_sel_hi:[1,0,1]
	v_pk_fma_f32 v[42:43], v[60:61], v[88:89], v[250:251] op_sel_hi:[1,0,1]
	v_pk_fma_f32 v[44:45], v[62:63], v[88:89], v[252:253] op_sel_hi:[1,0,1]
	v_pk_fma_f32 v[28:29], v[46:47], v[88:89], v[232:233] op_sel_hi:[1,0,1]
	v_pk_fma_f32 v[10:11], v[14:15], v[90:91], v[232:233] op_sel_hi:[1,0,1]
	v_pk_fma_f32 v[46:47], v[64:65], v[88:89], v[254:255] op_sel_hi:[1,0,1]
	v_pk_fma_f32 v[30:31], v[48:49], v[88:89], v[234:235] op_sel_hi:[1,0,1]
	v_pk_fma_f32 v[14:15], v[32:33], v[90:91], v[254:255] op_sel_hi:[1,0,1]
	v_pk_fma_f32 v[12:13], v[16:17], v[90:91], v[234:235] op_sel_hi:[1,0,1]
	v_mov_b32_e32 v210, 64
	v_xor_b32_e32 v211, 32, v209
	v_xor_b32_e32 v212, 16, v209
	v_xor_b32_e32 v213, 8, v209
	v_xor_b32_e32 v214, 4, v209
	v_xor_b32_e32 v215, 2, v209
	v_xor_b32_e32 v216, 1, v209
	v_mov_b32_e32 v217, 2
	v_mov_b32_e32 v222, 0x200
	v_mov_b32_e32 v223, 0x2000
	v_mov_b32_e32 v224, 0x461c4000
	v_mov_b32_e32 v225, 0x63
	s_and_saveexec_b64 s[2:3], vcc
	s_xor_b64 s[2:3], exec, s[2:3]
	s_cbranch_execz .LBB0_299
	v_cmp_lt_u32_e32 vcc, 47, v89
	v_cvt_pk_bf16_f32 v16, v84, s0
	v_cvt_pk_bf16_f32 v17, v85, s0
	v_cvt_pk_bf16_f32 v32, v86, s0
	v_cvt_pk_bf16_f32 v33, v87, s0
	s_and_saveexec_b64 s[8:9], vcc
	s_xor_b64 s[22:23], exec, s[8:9]
	s_cbranch_execz .LBB0_296
	s_mov_b32 s8, 0x5040100
	v_cvt_pk_bf16_f32 v61, v82, v83
	v_cvt_pk_bf16_f32 v60, v80, v81
	v_perm_b32 v33, v33, v32, s8
	v_perm_b32 v32, v17, v16, s8
	ds_write2_b64 v226, v[60:61], v[32:33] offset1:2
	v_cvt_pk_bf16_f32 v17, v42, v43
	v_cvt_pk_bf16_f32 v16, v58, v59
	v_cvt_pk_bf16_f32 v33, v46, v47
	v_cvt_pk_bf16_f32 v32, v44, v45
	ds_write2_b64 v226, v[16:17], v[32:33] offset0:4 offset1:6
	v_cvt_pk_bf16_f32 v17, v72, v73
	v_cvt_pk_bf16_f32 v16, v70, v71
	v_cvt_pk_bf16_f32 v33, v56, v57
	v_cvt_pk_bf16_f32 v32, v54, v55
	ds_write2_b64 v226, v[16:17], v[32:33] offset0:8 offset1:10
	v_cvt_pk_bf16_f32 v17, v26, v27
	v_cvt_pk_bf16_f32 v16, v40, v41
	v_cvt_pk_bf16_f32 v27, v30, v31
	v_cvt_pk_bf16_f32 v26, v28, v29
	ds_write2_b64 v226, v[16:17], v[26:27] offset0:12 offset1:14
	v_cvt_pk_bf16_f32 v17, v52, v53
	v_cvt_pk_bf16_f32 v16, v50, v51
	v_cvt_pk_bf16_f32 v25, v24, v25
	v_cvt_pk_bf16_f32 v24, v38, v39
	v_lshlrev_b64 v[48:49], 11, v[136:137]
	ds_write2_b64 v130, v[16:17], v[24:25] offset0:64 offset1:66
	v_cvt_pk_bf16_f32 v17, v22, v23
	v_cvt_pk_bf16_f32 v16, v20, v21
	v_cvt_pk_bf16_f32 v15, v14, v15
	v_cvt_pk_bf16_f32 v14, v18, v19
	v_lshl_add_u64 v[48:49], s[38:39], 0, v[48:49]
	v_mov_b32_e32 v139, v1
	ds_write2_b64 v130, v[16:17], v[14:15] offset0:68 offset1:70
	v_cvt_pk_bf16_f32 v15, v36, v37
	v_cvt_pk_bf16_f32 v14, v34, v35
	v_cvt_pk_bf16_f32 v9, v8, v9
	v_cvt_pk_bf16_f32 v8, v6, v7
	v_cvt_pk_bf16_f32 v5, v4, v5
	v_cvt_pk_bf16_f32 v4, v2, v3
	v_cvt_pk_bf16_f32 v3, v12, v13
	v_cvt_pk_bf16_f32 v2, v10, v11
	v_lshl_add_u64 v[48:49], v[138:139], 1, v[48:49]
	ds_write2_b64 v130, v[14:15], v[8:9] offset0:72 offset1:74
	ds_write2_b64 v130, v[4:5], v[2:3] offset0:76 offset1:78
	v_mov_b32_e32 v77, v1
	v_lshl_add_u64 v[2:3], v[48:49], 0, v[76:77]
	v_mov_b32_e32 v75, v1
	v_lshl_add_u64 v[10:11], v[2:3], 0, v[74:75]
	ds_read_b128 v[2:5], v227
	ds_read_b128 v[6:9], v227 offset:1152
	s_mov_b32 s8, 0x7ffe000
	v_add_co_u32_e32 v12, vcc, s8, v10
	s_mov_b32 s8, 0x8002000
	s_nop 0
	v_addc_co_u32_e32 v13, vcc, 0, v11, vcc
	s_waitcnt lgkmcnt(1)
	global_store_dwordx4 v[12:13], v[2:5], off offset:2176
	s_nop 1
	v_add_co_u32_e32 v2, vcc, s8, v10
	s_mov_b32 s8, 0x8006000
	s_nop 0
	v_addc_co_u32_e32 v3, vcc, 0, v11, vcc
	s_waitcnt lgkmcnt(0)
	global_store_dwordx4 v[2:3], v[6:9], off offset:2176
	ds_read_b128 v[2:5], v227 offset:2304
	ds_read_b128 v[6:9], v227 offset:3456
	v_add_co_u32_e32 v12, vcc, s8, v10
	s_mov_b32 s8, 0x800a000
	s_nop 0
	v_addc_co_u32_e32 v13, vcc, 0, v11, vcc
	s_waitcnt lgkmcnt(1)
	global_store_dwordx4 v[12:13], v[2:5], off offset:2176
	s_nop 1
	v_add_co_u32_e32 v2, vcc, s8, v10
	s_mov_b32 s8, 0x800e000
	s_nop 0
	v_addc_co_u32_e32 v3, vcc, 0, v11, vcc
	s_waitcnt lgkmcnt(0)
	global_store_dwordx4 v[2:3], v[6:9], off offset:2176
	ds_read_b128 v[2:5], v227 offset:4608
	ds_read_b128 v[6:9], v227 offset:5760
	v_add_co_u32_e32 v12, vcc, s8, v10
	s_nop 1
	v_addc_co_u32_e32 v13, vcc, 0, v11, vcc
	s_waitcnt lgkmcnt(1)
	global_store_dwordx4 v[12:13], v[2:5], off offset:2176
	s_nop 1
	v_add_co_u32_e32 v2, vcc, 0x8012000, v10
	s_nop 1
	v_addc_co_u32_e32 v3, vcc, 0, v11, vcc
	s_waitcnt lgkmcnt(0)
	global_store_dwordx4 v[2:3], v[6:9], off offset:2176
	ds_read_b128 v[2:5], v227 offset:6912
	ds_read_b128 v[6:9], v227 offset:8064
	v_add_co_u32_e32 v12, vcc, 0x8016000, v10
	s_nop 1
	v_addc_co_u32_e32 v13, vcc, 0, v11, vcc
	s_waitcnt lgkmcnt(1)
	global_store_dwordx4 v[12:13], v[2:5], off offset:2176
	s_nop 1
	v_add_co_u32_e32 v2, vcc, 0x801a000, v10
	s_nop 1
	v_addc_co_u32_e32 v3, vcc, 0, v11, vcc
	s_waitcnt lgkmcnt(0)
	global_store_dwordx4 v[2:3], v[6:9], off offset:2176
